# compression MLP first matmul: 18 operand loads per K step issued together instead of one L2 round trip per MFMA
# speedup vs baseline: 1.0077x; 1.0077x over previous
.LBB0_550:
	v_ashrrev_i32_e32 v59, 1, v58
	v_add_u32_e32 v59, v59, v53
	v_lshl_add_u64 v[60:61], v[54:55], 0, s[8:9]
	s_mov_b32 s13, 0x4b80000
	v_min_i32_e32 v59, 0x1fff, v59
	v_add_co_u32_e32 v90, vcc, s13, v60
	v_add_u32_e32 v59, s3, v59
	s_nop 0
	v_addc_co_u32_e32 v91, vcc, 0, v61, vcc
	v_mad_i64_i32 v[106:107], s[30:31], v59, s23, v[56:57]
	s_mov_b32 s13, 0x4b90000
	v_add_co_u32_e64 v94, s[44:45], s13, v60
	s_mov_b32 s13, 0x4ba0000
	s_nop 0
	v_addc_co_u32_e64 v95, vcc, 0, v61, s[44:45]
	v_add_co_u32_e64 v96, s[46:47], s13, v60
	s_mov_b32 s13, 0x4bb0000
	s_nop 0
	v_addc_co_u32_e64 v97, vcc, 0, v61, s[46:47]
	v_add_co_u32_e64 v98, s[48:49], s13, v60
	s_mov_b32 s13, 0x4bc0000
	s_nop 0
	v_addc_co_u32_e64 v99, vcc, 0, v61, s[48:49]
	v_add_co_u32_e64 v100, s[50:51], s13, v60
	s_mov_b32 s13, 0x4bd0000
	s_nop 0
	v_addc_co_u32_e64 v101, vcc, 0, v61, s[50:51]
	v_add_co_u32_e64 v102, s[52:53], s13, v60
	s_mov_b32 s13, 0x4be0000
	s_nop 0
	v_addc_co_u32_e64 v103, vcc, 0, v61, s[52:53]
	v_add_co_u32_e64 v104, s[54:55], s13, v60
	s_mov_b32 s13, 0x4bf0000
	s_nop 0
	v_addc_co_u32_e64 v105, vcc, 0, v61, s[54:55]
	v_add_co_u32_e64 v60, s[56:57], s13, v60
	s_add_u32 s8, s8, 0x80
	s_nop 0
	v_addc_co_u32_e64 v61, vcc, 0, v61, s[56:57]
	s_addc_u32 s9, s9, 0
	s_cmpk_eq_i32 s8, 0x200
	v_add_u32_e32 v58, 2, v58
	global_load_dwordx4 v[86:89], v[106:107], off
	global_load_dwordx4 v[82:85], v[106:107], off offset:64
	global_load_dwordx4 v[212:215], v[90:91], off
	global_load_dwordx4 v[216:219], v[94:95], off
	global_load_dwordx4 v[220:223], v[96:97], off
	global_load_dwordx4 v[224:227], v[98:99], off
	global_load_dwordx4 v[228:231], v[100:101], off
	global_load_dwordx4 v[232:235], v[102:103], off
	global_load_dwordx4 v[236:239], v[104:105], off
	global_load_dwordx4 v[240:243], v[60:61], off
	global_load_dwordx4 v[244:247], v[90:91], off offset:64
	global_load_dwordx4 v[248:251], v[94:95], off offset:64
	global_load_dwordx4 v[138:141], v[96:97], off offset:64
	global_load_dwordx4 v[142:145], v[98:99], off offset:64
	global_load_dwordx4 v[146:149], v[100:101], off offset:64
	global_load_dwordx4 v[150:153], v[102:103], off offset:64
	global_load_dwordx4 v[176:179], v[104:105], off offset:64
	global_load_dwordx4 v[180:183], v[60:61], off offset:64
	s_waitcnt vmcnt(8)
	v_mfma_f32_16x16x32_bf16 v[2:5], v[86:89], v[212:215], v[2:5]
	v_mfma_f32_16x16x32_bf16 v[6:9], v[86:89], v[216:219], v[6:9]
	v_mfma_f32_16x16x32_bf16 v[10:13], v[86:89], v[220:223], v[10:13]
	v_mfma_f32_16x16x32_bf16 v[14:17], v[86:89], v[224:227], v[14:17]
	v_mfma_f32_16x16x32_bf16 v[18:21], v[86:89], v[228:231], v[18:21]
	v_mfma_f32_16x16x32_bf16 v[22:25], v[86:89], v[232:235], v[22:25]
	v_mfma_f32_16x16x32_bf16 v[26:29], v[86:89], v[236:239], v[26:29]
	v_mfma_f32_16x16x32_bf16 v[30:33], v[86:89], v[240:243], v[30:33]
	s_waitcnt vmcnt(0)
	v_mfma_f32_16x16x32_bf16 v[2:5], v[82:85], v[244:247], v[2:5]
	v_mfma_f32_16x16x32_bf16 v[6:9], v[82:85], v[248:251], v[6:9]
	v_mfma_f32_16x16x32_bf16 v[10:13], v[82:85], v[138:141], v[10:13]
	v_mfma_f32_16x16x32_bf16 v[14:17], v[82:85], v[142:145], v[14:17]
	v_mfma_f32_16x16x32_bf16 v[18:21], v[82:85], v[146:149], v[18:21]
	v_mfma_f32_16x16x32_bf16 v[22:25], v[82:85], v[150:153], v[22:25]
	v_mfma_f32_16x16x32_bf16 v[26:29], v[82:85], v[176:179], v[26:29]
	v_mfma_f32_16x16x32_bf16 v[30:33], v[82:85], v[180:183], v[30:33]
	s_cbranch_scc0 .LBB0_550
	v_add_u32_e32 v53, 0x4000, v79
	ds_write2_b32 v53, v2, v6 offset1:16
	ds_write2_b32 v53, v3, v7 offset0:132 offset1:148
	v_add_u32_e32 v2, 0x4400, v79
	ds_write2_b32 v2, v4, v8 offset0:8 offset1:24
	ds_write2_b32 v2, v5, v9 offset0:140 offset1:156
	ds_write2_b32 v53, v10, v14 offset0:32 offset1:48
	ds_write2_b32 v53, v11, v15 offset0:164 offset1:180
	ds_write2_b32 v2, v12, v16 offset0:40 offset1:56
	ds_write2_b32 v2, v13, v17 offset0:172 offset1:188
	ds_write2_b32 v53, v18, v22 offset0:64 offset1:80
	ds_write2_b32 v53, v19, v23 offset0:196 offset1:212
	ds_write2_b32 v2, v20, v24 offset0:72 offset1:88
	ds_write2_b32 v2, v21, v25 offset0:204 offset1:220
	ds_write2_b32 v53, v26, v30 offset0:96 offset1:112
	ds_write2_b32 v53, v27, v31 offset0:228 offset1:244
	ds_write2_b32 v2, v28, v32 offset0:104 offset1:120
	ds_write2_b32 v2, v29, v33 offset0:236 offset1:252
	s_waitcnt lgkmcnt(0)
	s_barrier
	ds_read_b128 v[2:5], v74 offset:16384
	s_movk_i32 s8, 0x7fff
	s_waitcnt lgkmcnt(0)
	v_pk_add_f32 v[6:7], v[4:5], 0 op_sel_hi:[1,0]
	v_pk_add_f32 v[8:9], v[2:3], 0 op_sel_hi:[1,0]
	ds_read_b128 v[2:5], v74 offset:24832
	s_waitcnt lgkmcnt(0)
	v_pk_add_f32 v[6:7], v[6:7], v[4:5]
	v_pk_add_f32 v[8:9], v[8:9], v[2:3]
	ds_read_b128 v[2:5], v74 offset:33280
	s_waitcnt lgkmcnt(0)
	v_pk_add_f32 v[6:7], v[6:7], v[4:5]
	v_pk_add_f32 v[8:9], v[8:9], v[2:3]
	ds_read_b128 v[2:5], v74 offset:41728
	s_waitcnt lgkmcnt(0)
	v_pk_add_f32 v[6:7], v[6:7], v[4:5]
	v_pk_add_f32 v[8:9], v[8:9], v[2:3]
	ds_read_b128 v[2:5], v74 offset:50176
	s_waitcnt lgkmcnt(0)
	v_pk_add_f32 v[6:7], v[6:7], v[4:5]
	v_pk_add_f32 v[8:9], v[8:9], v[2:3]
	ds_read_b128 v[2:5], v74 offset:58624
	s_waitcnt lgkmcnt(0)
	v_pk_add_f32 v[6:7], v[6:7], v[4:5]
	v_pk_add_f32 v[8:9], v[8:9], v[2:3]
	ds_read_b128 v[2:5], v75 offset:50688
	s_waitcnt lgkmcnt(0)
	v_pk_add_f32 v[6:7], v[6:7], v[4:5]
	v_pk_add_f32 v[8:9], v[8:9], v[2:3]
	ds_read_b128 v[2:5], v75 offset:59136
	s_waitcnt lgkmcnt(0)
	v_pk_add_f32 v[8:9], v[8:9], v[2:3]
	v_or_b32_e32 v2, s2, v73
	v_ashrrev_i32_e32 v3, 31, v2
	v_lshl_add_u64 v[2:3], v[2:3], 2, s[14:15]
	v_pk_add_f32 v[6:7], v[6:7], v[4:5]
	global_load_dwordx4 v[2:5], v[2:3], off
	s_waitcnt vmcnt(0)
	v_mov_b32_e32 v10, v3
	v_mov_b32_e32 v11, v4
	v_mov_b32_e32 v3, v5
	v_mov_b32_e32 v5, v7
	v_pk_mov_b32 v[6:7], v[8:9], v[6:7] op_sel:[1,0]
	v_mov_b32_e32 v4, v8
	v_pk_add_f32 v[6:7], v[6:7], v[10:11]
	v_pk_add_f32 v[2:3], v[2:3], v[4:5]
	v_mul_f32_e32 v5, 0x3d372713, v6
	v_mul_f32_e32 v5, v6, v5
	v_fma_f32 v5, v6, v5, v6
	v_mul_f32_e32 v5, 0x3f4c422a, v5
	v_add_f32_e32 v5, v5, v5
	v_mul_f32_e32 v5, 0x3fb8aa3b, v5
	v_exp_f32_e32 v8, v5
	v_mul_f32_e32 v5, 0x3d372713, v7
	v_mul_f32_e32 v5, v7, v5
	v_fma_f32 v5, v7, v5, v7
	v_mul_f32_e32 v5, 0x3f4c422a, v5
	v_add_f32_e32 v5, v5, v5
	v_mul_f32_e32 v5, 0x3fb8aa3b, v5
	v_exp_f32_e32 v9, v5
	v_pk_mul_f32 v[6:7], v[6:7], 0.5 op_sel_hi:[1,0]
	v_mul_f32_e32 v4, 0x3d372713, v2
	v_mul_f32_e32 v4, v2, v4
	v_pk_add_f32 v[8:9], v[8:9], 1.0 op_sel_hi:[1,0]
	v_fma_f32 v4, v2, v4, v2
	v_div_scale_f32 v5, s[2:3], v9, v9, 2.0
	v_rcp_f32_e32 v10, v5
	v_mul_f32_e32 v4, 0x3f4c422a, v4
	v_add_f32_e32 v4, v4, v4
	v_mul_f32_e32 v4, 0x3fb8aa3b, v4
	v_fma_f32 v11, -v5, v10, 1.0
	v_fmac_f32_e32 v10, v11, v10
	v_div_scale_f32 v11, vcc, 2.0, v9, 2.0
	v_mul_f32_e32 v12, v11, v10
	v_fma_f32 v13, -v5, v12, v11
	v_fmac_f32_e32 v12, v13, v10
	v_fma_f32 v5, -v5, v12, v11
	v_div_fmas_f32 v5, v5, v10, v12
	v_div_fixup_f32 v9, v5, v9, 2.0
	v_div_scale_f32 v5, s[2:3], v8, v8, 2.0
	v_rcp_f32_e32 v10, v5
	v_exp_f32_e32 v4, v4
	v_fma_f32 v11, -v5, v10, 1.0
	v_fmac_f32_e32 v10, v11, v10
	v_div_scale_f32 v11, vcc, 2.0, v8, 2.0
	v_mul_f32_e32 v12, v11, v10
	v_fma_f32 v13, -v5, v12, v11
	v_fmac_f32_e32 v12, v13, v10
	v_fma_f32 v5, -v5, v12, v11
	v_div_fmas_f32 v5, v5, v10, v12
	v_div_fixup_f32 v8, v5, v8, 2.0
	v_pk_add_f32 v[8:9], v[8:9], 1.0 op_sel_hi:[1,0] neg_lo:[1,0] neg_hi:[1,0]
	s_nop 0
	v_pk_add_f32 v[8:9], v[8:9], 1.0 op_sel_hi:[1,0]
	s_nop 0
	v_pk_mul_f32 v[6:7], v[6:7], v[8:9]
	s_nop 0
	v_and_b32_sdwa v5, v7, v194 dst_sel:DWORD dst_unused:UNUSED_PAD src0_sel:WORD_1 src1_sel:DWORD
	v_and_b32_sdwa v8, v6, v194 dst_sel:DWORD dst_unused:UNUSED_PAD src0_sel:WORD_1 src1_sel:DWORD
	v_add3_u32 v7, v7, v5, s8
	v_add3_u32 v5, v6, v8, s8
	v_and_b32_e32 v6, 0xffff0000, v5
	v_mul_f32_e32 v5, 0x3d372713, v3
	v_mul_f32_e32 v5, v3, v5
	v_fma_f32 v5, v3, v5, v3
	v_mul_f32_e32 v5, 0x3f4c422a, v5
	v_add_f32_e32 v5, v5, v5
	v_mul_f32_e32 v5, 0x3fb8aa3b, v5
	v_exp_f32_e32 v5, v5
	v_pk_mul_f32 v[2:3], v[2:3], 0.5 op_sel_hi:[1,0]
	v_pk_add_f32 v[4:5], v[4:5], 1.0 op_sel_hi:[1,0]
	s_nop 0
	v_div_scale_f32 v8, s[2:3], v5, v5, 2.0
	v_rcp_f32_e32 v9, v8
	s_nop 0
	v_fma_f32 v10, -v8, v9, 1.0
	v_fmac_f32_e32 v9, v10, v9
	v_div_scale_f32 v10, vcc, 2.0, v5, 2.0
	v_mul_f32_e32 v11, v10, v9
	v_fma_f32 v12, -v8, v11, v10
	v_fmac_f32_e32 v11, v12, v9
	v_fma_f32 v8, -v8, v11, v10
	v_div_fmas_f32 v8, v8, v9, v11
	v_div_fixup_f32 v5, v8, v5, 2.0
	v_div_scale_f32 v8, s[2:3], v4, v4, 2.0
	v_rcp_f32_e32 v9, v8
	s_nop 0
	v_fma_f32 v10, -v8, v9, 1.0
	v_fmac_f32_e32 v9, v10, v9
	v_div_scale_f32 v10, vcc, 2.0, v4, 2.0
	v_mul_f32_e32 v11, v10, v9
	v_fma_f32 v12, -v8, v11, v10
	v_fmac_f32_e32 v11, v12, v9
	v_fma_f32 v8, -v8, v11, v10
	v_div_fmas_f32 v8, v8, v9, v11
	v_div_fixup_f32 v4, v8, v4, 2.0
	v_pk_add_f32 v[4:5], v[4:5], 1.0 op_sel_hi:[1,0] neg_lo:[1,0] neg_hi:[1,0]
	s_nop 0
	v_pk_add_f32 v[4:5], v[4:5], 1.0 op_sel_hi:[1,0]
	s_nop 0
	v_pk_mul_f32 v[2:3], v[2:3], v[4:5]
	s_nop 0
	v_and_b32_sdwa v4, v3, v194 dst_sel:DWORD dst_unused:UNUSED_PAD src0_sel:WORD_1 src1_sel:DWORD
	v_and_b32_sdwa v5, v2, v194 dst_sel:DWORD dst_unused:UNUSED_PAD src0_sel:WORD_1 src1_sel:DWORD
	v_add3_u32 v3, v3, v4, s8
	v_add3_u32 v2, v2, v5, s8
	v_and_b32_e32 v3, 0xffff0000, v3
	v_or_b32_sdwa v3, v3, v7 dst_sel:DWORD dst_unused:UNUSED_PAD src0_sel:DWORD src1_sel:WORD_1
	v_or_b32_sdwa v2, v2, v6 dst_sel:DWORD dst_unused:UNUSED_PAD src0_sel:WORD_1 src1_sel:DWORD
	ds_write_b64 v76, v[2:3]
	s_waitcnt lgkmcnt(0)
	s_barrier
	s_and_saveexec_b64 s[2:3], s[34:35]
	s_cbranch_execz .LBB0_553
	s_ashr_i32 s8, s16, 7
	s_ashr_i32 s9, s8, 31
	s_lshl_b64 s[8:9], s[8:9], 15
	v_lshl_add_u64 v[14:15], v[48:49], 0, s[8:9]
	ds_read_b128 v[2:5], v77
	global_load_dword v6, v[14:15], off
	global_load_dword v7, v[14:15], off offset:256
	global_load_dword v8, v[14:15], off offset:512
	global_load_dword v9, v[14:15], off offset:768
	global_load_dword v10, v[14:15], off offset:1024
	global_load_dword v11, v[14:15], off offset:1280
	global_load_dword v12, v[14:15], off offset:1536
	global_load_dword v13, v[14:15], off offset:1792
	s_movk_i32 s8, 0x2000
	s_waitcnt vmcnt(6)
	v_cvt_pk_bf16_f32 v6, v6, v7
	s_waitcnt vmcnt(4)
	v_cvt_pk_bf16_f32 v7, v8, v9
	s_waitcnt vmcnt(2)
	v_cvt_pk_bf16_f32 v8, v10, v11
	v_add_co_u32_e32 v10, vcc, s8, v14
	s_waitcnt vmcnt(0)
	v_cvt_pk_bf16_f32 v9, v12, v13
	v_addc_co_u32_e32 v11, vcc, 0, v15, vcc
	s_waitcnt lgkmcnt(0)
	v_mfma_f32_16x16x32_bf16 v[2:5], v[2:5], v[6:9], 0
	ds_read_b128 v[6:9], v77 offset:64
	global_load_dword v12, v[10:11], off
	global_load_dword v13, v[10:11], off offset:256
	global_load_dword v16, v[10:11], off offset:512
	global_load_dword v17, v[10:11], off offset:768
	global_load_dword v18, v[10:11], off offset:1024
	global_load_dword v19, v[10:11], off offset:1280
	global_load_dword v20, v[10:11], off offset:1536
	global_load_dword v21, v[10:11], off offset:1792
	s_movk_i32 s8, 0x4000
	s_waitcnt vmcnt(6)
	v_cvt_pk_bf16_f32 v10, v12, v13
	s_waitcnt vmcnt(4)
	v_cvt_pk_bf16_f32 v11, v16, v17
	s_waitcnt vmcnt(2)
	v_cvt_pk_bf16_f32 v12, v18, v19
	s_waitcnt vmcnt(0)
	v_cvt_pk_bf16_f32 v13, v20, v21
	s_waitcnt lgkmcnt(0)
	s_nop 0
	v_mfma_f32_16x16x32_bf16 v[2:5], v[6:9], v[10:13], v[2:5]
	v_add_co_u32_e32 v10, vcc, s8, v14
	ds_read_b128 v[6:9], v77 offset:128
	s_nop 0
	v_addc_co_u32_e32 v11, vcc, 0, v15, vcc
	global_load_dword v12, v[10:11], off
	global_load_dword v13, v[10:11], off offset:256
	global_load_dword v16, v[10:11], off offset:512
	global_load_dword v17, v[10:11], off offset:768
	global_load_dword v18, v[10:11], off offset:1024
	global_load_dword v19, v[10:11], off offset:1280
	global_load_dword v20, v[10:11], off offset:1536
	global_load_dword v21, v[10:11], off offset:1792
	s_movk_i32 s8, 0x6000
	s_waitcnt vmcnt(6)
	v_cvt_pk_bf16_f32 v10, v12, v13
	s_waitcnt vmcnt(4)
	v_cvt_pk_bf16_f32 v11, v16, v17
	s_waitcnt vmcnt(2)
	v_cvt_pk_bf16_f32 v12, v18, v19
	s_waitcnt vmcnt(0)
	v_cvt_pk_bf16_f32 v13, v20, v21
	s_waitcnt lgkmcnt(0)
	s_nop 0
	v_mfma_f32_16x16x32_bf16 v[2:5], v[6:9], v[10:13], v[2:5]
	v_add_co_u32_e32 v10, vcc, s8, v14
	ds_read_b128 v[6:9], v77 offset:192
	s_nop 0
	v_addc_co_u32_e32 v11, vcc, 0, v15, vcc
	global_load_dword v12, v[10:11], off
	global_load_dword v13, v[10:11], off offset:256
	global_load_dword v14, v[10:11], off offset:512
	global_load_dword v15, v[10:11], off offset:768
	global_load_dword v16, v[10:11], off offset:1024
	global_load_dword v17, v[10:11], off offset:1280
	global_load_dword v18, v[10:11], off offset:1536
	global_load_dword v19, v[10:11], off offset:1792
	s_waitcnt vmcnt(6)
	v_cvt_pk_bf16_f32 v10, v12, v13
	s_waitcnt vmcnt(4)
	v_cvt_pk_bf16_f32 v11, v14, v15
	s_waitcnt vmcnt(2)
	v_cvt_pk_bf16_f32 v12, v16, v17
	s_waitcnt vmcnt(0)
	v_cvt_pk_bf16_f32 v13, v18, v19
	s_waitcnt lgkmcnt(0)
	s_nop 0
	v_mfma_f32_16x16x32_bf16 v[2:5], v[6:9], v[10:13], v[2:5]
	v_add_u32_e32 v6, 0x2000, v80
	s_nop 6
	ds_write2_b32 v6, v2, v3 offset1:65
	ds_write2_b32 v6, v4, v5 offset0:130 offset1:195
